# v7 + XCD-local P7->P8 seam + EpiKV V^T outputs transposed through LDS for 16-byte stores
# baseline (speedup 1.0000x reference)
.LBB0_1288:
	v_lshrrev_b32_e32 v200, 6, v220
	v_lshlrev_b32_e32 v200, 10, v200
	v_add_u32_e32 v200, 0x21000, v200
	v_lshl_add_u32 v201, v225, 4, v200
	v_lshrrev_b32_e32 v202, 4, v225
	v_and_b32_e32 v203, 15, v225
	v_lshlrev_b32_e32 v202, 8, v202
	v_lshl_add_u32 v202, v203, 1, v202
	v_add_u32_e32 v200, v200, v202
	v_bfe_u32 v202, v203, 1, 3
	v_lshlrev_b32_e32 v202, 13, v202
	v_and_b32_e32 v204, 1, v203
	v_lshl_add_u32 v202, v204, 4, v202
	v_lshlrev_b32_e32 v204, 1, v203
	v_sub_u32_e32 v202, v202, v204
	v_mov_b32_e32 v203, 0
	s_lshl_b32 s8, s35, 8
	v_mov_b32_e32 v96, v163
	v_mov_b32_e32 v196, v162
	s_add_i32 s8, s8, s88
	s_nop 0
	v_add_u32_e32 v160, s8, v96
	v_lshlrev_b32_e32 v142, 2, v196
	v_ashrrev_i32_e32 v143, 31, v142
	v_ashrrev_i32_e32 v161, 31, v160
	v_add_u32_e32 v154, 16, v160
	v_lshl_add_u64 v[190:191], v[142:143], 2, s[58:59]
	v_lshlrev_b64 v[142:143], 5, v[160:161]
	v_ashrrev_i32_e32 v155, 31, v154
	v_add_u32_e32 v152, 32, v160
	v_lshl_add_u64 v[142:143], v[190:191], 0, v[142:143]
	v_lshlrev_b64 v[144:145], 5, v[154:155]
	v_ashrrev_i32_e32 v153, 31, v152
	v_add_u32_e32 v150, 48, v160
	v_lshl_add_u64 v[144:145], v[190:191], 0, v[144:145]
	global_load_dwordx4 v[156:159], v[142:143], off
	global_load_dwordx4 v[166:169], v[144:145], off
	v_lshlrev_b64 v[142:143], 5, v[152:153]
	v_ashrrev_i32_e32 v151, 31, v150
	v_lshl_add_u64 v[142:143], v[190:191], 0, v[142:143]
	v_lshlrev_b64 v[144:145], 5, v[150:151]
	v_lshl_add_u64 v[144:145], v[190:191], 0, v[144:145]
	global_load_dwordx4 v[170:173], v[142:143], off
	global_load_dwordx4 v[174:177], v[144:145], off
	v_add_u32_e32 v148, 0x80, v160
	v_ashrrev_i32_e32 v149, 31, v148
	v_lshlrev_b64 v[142:143], 5, v[148:149]
	v_lshl_add_u64 v[142:143], v[190:191], 0, v[142:143]
	v_add_u32_e32 v146, 0x90, v160
	global_load_dwordx4 v[178:181], v[142:143], off
	v_ashrrev_i32_e32 v147, 31, v146
	v_lshlrev_b64 v[142:143], 5, v[146:147]
	v_lshl_add_u64 v[142:143], v[190:191], 0, v[142:143]
	v_add_u32_e32 v144, 0xa0, v160
	global_load_dwordx4 v[182:185], v[142:143], off
	v_ashrrev_i32_e32 v145, 31, v144
	v_lshlrev_b64 v[142:143], 5, v[144:145]
	v_lshl_add_u64 v[142:143], v[190:191], 0, v[142:143]
	global_load_dwordx4 v[186:189], v[142:143], off
	v_add_u32_e32 v142, 0xb0, v160
	v_ashrrev_i32_e32 v143, 31, v142
	v_lshlrev_b64 v[192:193], 5, v[142:143]
	v_lshl_add_u64 v[190:191], v[190:191], 0, v[192:193]
	global_load_dwordx4 v[190:193], v[190:191], off
	v_and_b32_e32 v143, 64, v225
	v_xor_b32_e32 v96, 16, v225
	v_add_u32_e32 v143, 64, v143
	v_cmp_gt_i32_e32 vcc, 2, v196
	v_xor_b32_e32 v145, 32, v225
	s_waitcnt vmcnt(0)
	v_mov_b32_e32 v194, v157
	v_cndmask_b32_e64 v147, 0, 1.0, vcc
	v_cmp_lt_i32_e32 vcc, v96, v143
	v_mov_b32_e32 v195, v158
	v_mov_b32_e32 v157, v159
	v_cndmask_b32_e32 v96, v225, v96, vcc
	v_cmp_lt_i32_e32 vcc, v145, v143
	v_pk_add_f32 v[156:157], v[194:195], v[156:157]
	v_add_f32_e32 v149, v168, v169
	v_cndmask_b32_e32 v143, v225, v145, vcc
	v_add_f32_e32 v145, v166, v167
	v_add_f32_e32 v151, v170, v171
	v_add_f32_e32 v153, v172, v173
	v_add_f32_e32 v155, v174, v175
	v_add_f32_e32 v158, v176, v177
	v_add_f32_e32 v156, v156, v157
	v_lshlrev_b32_e32 v96, 2, v96
	v_add_f32_e32 v145, v145, v149
	v_add_f32_e32 v149, v151, v153
	v_add_f32_e32 v151, v155, v158
	v_mul_f32_e32 v155, v147, v156
	v_mul_f32_e32 v158, v147, v145
	ds_bpermute_b32 v155, v96, v155
	ds_bpermute_b32 v173, v96, v158
	v_lshlrev_b32_e32 v143, 2, v143
	v_add_f32_e32 v159, v178, v179
	v_add_f32_e32 v161, v180, v181
	s_waitcnt lgkmcnt(0)
	v_fmac_f32_e32 v155, v147, v156
	v_fmac_f32_e32 v173, v147, v145
	ds_bpermute_b32 v145, v143, v155
	v_add_f32_e32 v153, v159, v161
	v_mul_f32_e32 v159, v147, v149
	ds_bpermute_b32 v171, v96, v159
	v_add_f32_e32 v166, v182, v183
	v_add_f32_e32 v167, v184, v185
	v_add_f32_e32 v157, v166, v167
	v_mul_f32_e32 v161, v147, v151
	v_mul_f32_e32 v166, v147, v153
	ds_bpermute_b32 v169, v96, v161
	ds_bpermute_b32 v167, v96, v166
	s_waitcnt lgkmcnt(3)
	v_add_f32_e32 v145, v155, v145
	v_fmamk_f32 v145, v145, 0x3b800000, v226
	s_waitcnt lgkmcnt(2)
	v_fmac_f32_e32 v171, v147, v149
	v_rsq_f32_e32 v156, v145
	v_add_f32_e32 v145, v186, v187
	v_add_f32_e32 v149, v188, v189
	v_add_f32_e32 v149, v145, v149
	v_mul_f32_e32 v145, v147, v149
	s_waitcnt lgkmcnt(1)
	v_fmac_f32_e32 v169, v147, v151
	s_waitcnt lgkmcnt(0)
	v_fmac_f32_e32 v167, v147, v153
	ds_bpermute_b32 v151, v96, v145
	v_add_f32_e32 v145, v190, v191
	v_add_f32_e32 v153, v192, v193
	v_add_f32_e32 v158, v145, v153
	v_mul_f32_e32 v175, v147, v157
	v_mul_f32_e32 v145, v147, v158
	ds_bpermute_b32 v155, v96, v175
	ds_bpermute_b32 v145, v96, v145
	s_waitcnt lgkmcnt(2)
	v_fmac_f32_e32 v151, v147, v149
	ds_bpermute_b32 v174, v143, v173
	ds_bpermute_b32 v172, v143, v171
	s_waitcnt lgkmcnt(3)
	v_fmac_f32_e32 v155, v147, v157
	s_waitcnt lgkmcnt(2)
	v_fmac_f32_e32 v145, v147, v158
	ds_bpermute_b32 v170, v143, v169
	ds_bpermute_b32 v168, v143, v167
	ds_bpermute_b32 v166, v143, v155
	ds_bpermute_b32 v153, v143, v151
	ds_bpermute_b32 v147, v143, v145
	v_lshl_add_u32 v96, v196, 3, s89
	v_lshl_add_u32 v177, s96, 8, v96
	v_and_b32_e32 v175, 0xfff, v160
	v_ashrrev_i32_e32 v143, 9, v160
	v_pk_mul_f32 v[158:159], v[128:129], v[156:157] op_sel_hi:[1,0]
	v_pk_mul_f32 v[128:129], v[122:123], v[156:157] op_sel_hi:[1,0]
	v_add_u32_e32 v122, 0xfffffe00, v177
	v_lshlrev_b32_e32 v123, 13, v96
	v_and_b32_e32 v176, -8, v143
	v_pk_mul_f32 v[160:161], v[126:127], v[156:157] op_sel_hi:[1,0]
	v_pk_mul_f32 v[126:127], v[124:125], v[156:157] op_sel_hi:[1,0]
	v_cmp_lt_i32_e64 s[8:9], s60, v177
	v_lshrrev_b32_e32 v143, 6, v122
	v_and_b32_e32 v122, 0x70000, v123
	v_lshlrev_b32_e32 v124, 1, v175
	s_and_saveexec_b64 s[10:11], s[8:9]
	s_xor_b64 s[10:11], exec, s[10:11]
	s_cbranch_execz .LBB0_1290
	v_add_u32_e32 v178, v143, v176
	v_ashrrev_i32_e32 v179, 31, v178
	v_lshlrev_b64 v[178:179], 19, v[178:179]
	v_lshl_add_u64 v[178:179], s[54:55], 0, v[178:179]
	v_mov_b32_e32 v123, v97
	v_lshl_add_u64 v[178:179], v[178:179], 0, v[122:123]
	v_mov_b32_e32 v125, v97
	v_lshl_add_u64 v[178:179], v[178:179], 0, v[124:125]
	s_movk_i32 s22, 0x4000
	s_movk_i32 s22, 0x6000
	s_mov_b32 s22, 0xa000
	v_cvt_pk_bf16_f32 v204, v160, s0
	ds_write_b16 v200, v204
	v_cvt_pk_bf16_f32 v204, v161, s0
	ds_write_b16 v200, v204 offset:32
	v_cvt_pk_bf16_f32 v204, v158, s0
	ds_write_b16 v200, v204 offset:64
	v_cvt_pk_bf16_f32 v204, v159, s0
	ds_write_b16 v200, v204 offset:96
	v_cvt_pk_bf16_f32 v204, v128, s0
	ds_write_b16 v200, v204 offset:128
	v_cvt_pk_bf16_f32 v204, v129, s0
	ds_write_b16 v200, v204 offset:160
	v_cvt_pk_bf16_f32 v204, v126, s0
	ds_write_b16 v200, v204 offset:192
	v_cvt_pk_bf16_f32 v204, v127, s0
	ds_write_b16 v200, v204 offset:224
	s_waitcnt lgkmcnt(0)
	ds_read_b128 v[208:211], v201
	v_lshl_add_u64 v[206:207], v[178:179], 0, v[202:203]
	s_waitcnt lgkmcnt(0)
	global_store_dwordx4 v[206:207], v[208:211], off

.LBB0_1292:
	s_or_b64 exec, exec, s[10:11]
	v_mov_b32_e32 v157, v156
	v_pk_mul_f32 v[126:127], v[118:119], v[156:157]
	v_pk_mul_f32 v[118:119], v[114:115], v[156:157]
	v_pk_mul_f32 v[114:115], v[116:117], v[156:157]
	v_add_u32_e32 v116, 0x80, v177
	v_add_u32_e32 v117, 0xfffffe80, v177
	v_pk_mul_f32 v[120:121], v[120:121], v[156:157]
	v_cmp_lt_i32_e64 s[10:11], s60, v116
	v_lshrrev_b32_e32 v128, 6, v117
	s_and_saveexec_b64 s[22:23], s[10:11]
	s_xor_b64 s[76:77], exec, s[22:23]
	s_cbranch_execz .LBB0_1294
	v_add_u32_e32 v156, v128, v176
	v_ashrrev_i32_e32 v157, 31, v156
	v_lshlrev_b64 v[156:157], 19, v[156:157]
	v_lshl_add_u64 v[156:157], s[54:55], 0, v[156:157]
	v_mov_b32_e32 v123, v97
	v_lshl_add_u64 v[156:157], v[156:157], 0, v[122:123]
	v_mov_b32_e32 v125, v97
	v_lshl_add_u64 v[124:125], v[156:157], 0, v[124:125]
	s_movk_i32 s22, 0x4000
	s_movk_i32 s22, 0x6000
	v_cvt_pk_bf16_f32 v204, v126, s0
	ds_write_b16 v200, v204
	v_cvt_pk_bf16_f32 v204, v127, s0
	ds_write_b16 v200, v204 offset:32
	v_cvt_pk_bf16_f32 v204, v120, s0
	ds_write_b16 v200, v204 offset:64
	v_cvt_pk_bf16_f32 v204, v121, s0
	ds_write_b16 v200, v204 offset:96
	v_cvt_pk_bf16_f32 v204, v118, s0
	ds_write_b16 v200, v204 offset:128
	v_cvt_pk_bf16_f32 v204, v119, s0
	ds_write_b16 v200, v204 offset:160
	v_cvt_pk_bf16_f32 v204, v114, s0
	ds_write_b16 v200, v204 offset:192
	v_cvt_pk_bf16_f32 v204, v115, s0
	ds_write_b16 v200, v204 offset:224
	s_waitcnt lgkmcnt(0)
	ds_read_b128 v[208:211], v201
	v_lshl_add_u64 v[206:207], v[124:125], 0, v[202:203]
	s_waitcnt lgkmcnt(0)
	global_store_dwordx4 v[206:207], v[208:211], off

.LBB0_1296:
	s_or_b64 exec, exec, s[76:77]
	s_waitcnt lgkmcnt(6)
	v_add_f32_e32 v114, v173, v174
	v_fmamk_f32 v114, v114, 0x3b800000, v226
	v_rsq_f32_e32 v114, v114
	v_and_b32_e32 v118, 0xfff, v154
	v_ashrrev_i32_e32 v115, 9, v154
	v_and_b32_e32 v119, -8, v115
	v_pk_mul_f32 v[116:117], v[110:111], v[114:115] op_sel_hi:[1,0]
	v_pk_mul_f32 v[112:113], v[112:113], v[114:115] op_sel_hi:[1,0]
	v_pk_mul_f32 v[110:111], v[106:107], v[114:115] op_sel_hi:[1,0]
	v_pk_mul_f32 v[108:109], v[108:109], v[114:115] op_sel_hi:[1,0]
	v_lshlrev_b32_e32 v106, 1, v118
	s_and_saveexec_b64 s[22:23], s[8:9]
	s_xor_b64 s[76:77], exec, s[22:23]
	s_cbranch_execz .LBB0_1298
	v_add_u32_e32 v120, v143, v119
	v_ashrrev_i32_e32 v121, 31, v120
	v_lshlrev_b64 v[120:121], 19, v[120:121]
	v_lshl_add_u64 v[120:121], s[54:55], 0, v[120:121]
	v_mov_b32_e32 v123, v97
	v_lshl_add_u64 v[120:121], v[120:121], 0, v[122:123]
	v_mov_b32_e32 v107, v97
	v_lshl_add_u64 v[120:121], v[120:121], 0, v[106:107]
	s_movk_i32 s22, 0x4000
	s_movk_i32 s22, 0x6000
	v_cvt_pk_bf16_f32 v204, v116, s0
	ds_write_b16 v200, v204
	v_cvt_pk_bf16_f32 v204, v117, s0
	ds_write_b16 v200, v204 offset:32
	v_cvt_pk_bf16_f32 v204, v112, s0
	ds_write_b16 v200, v204 offset:64
	v_cvt_pk_bf16_f32 v204, v113, s0
	ds_write_b16 v200, v204 offset:96
	v_cvt_pk_bf16_f32 v204, v110, s0
	ds_write_b16 v200, v204 offset:128
	v_cvt_pk_bf16_f32 v204, v111, s0
	ds_write_b16 v200, v204 offset:160
	v_cvt_pk_bf16_f32 v204, v108, s0
	ds_write_b16 v200, v204 offset:192
	v_cvt_pk_bf16_f32 v204, v109, s0
	ds_write_b16 v200, v204 offset:224
	s_waitcnt lgkmcnt(0)
	ds_read_b128 v[208:211], v201
	v_lshl_add_u64 v[206:207], v[120:121], 0, v[202:203]
	s_waitcnt lgkmcnt(0)
	global_store_dwordx4 v[206:207], v[208:211], off

.LBB0_1300:
	s_or_b64 exec, exec, s[76:77]
	v_mov_b32_e32 v115, v114
	v_pk_mul_f32 v[108:109], v[102:103], v[114:115]
	v_pk_mul_f32 v[104:105], v[104:105], v[114:115]
	v_pk_mul_f32 v[102:103], v[98:99], v[114:115]
	v_pk_mul_f32 v[98:99], v[100:101], v[114:115]
	s_and_saveexec_b64 s[22:23], s[10:11]
	s_xor_b64 s[76:77], exec, s[22:23]
	s_cbranch_execz .LBB0_1302
	v_add_u32_e32 v100, v128, v119
	v_ashrrev_i32_e32 v101, 31, v100
	v_lshlrev_b64 v[100:101], 19, v[100:101]
	v_lshl_add_u64 v[100:101], s[54:55], 0, v[100:101]
	v_mov_b32_e32 v123, v97
	v_lshl_add_u64 v[100:101], v[100:101], 0, v[122:123]
	v_mov_b32_e32 v107, v97
	v_lshl_add_u64 v[100:101], v[100:101], 0, v[106:107]
	s_movk_i32 s22, 0x4000
	s_movk_i32 s22, 0x6000
	v_cvt_pk_bf16_f32 v204, v108, s0
	ds_write_b16 v200, v204
	v_cvt_pk_bf16_f32 v204, v109, s0
	ds_write_b16 v200, v204 offset:32
	v_cvt_pk_bf16_f32 v204, v104, s0
	ds_write_b16 v200, v204 offset:64
	v_cvt_pk_bf16_f32 v204, v105, s0
	ds_write_b16 v200, v204 offset:96
	v_cvt_pk_bf16_f32 v204, v102, s0
	ds_write_b16 v200, v204 offset:128
	v_cvt_pk_bf16_f32 v204, v103, s0
	ds_write_b16 v200, v204 offset:160
	v_cvt_pk_bf16_f32 v204, v98, s0
	ds_write_b16 v200, v204 offset:192
	v_cvt_pk_bf16_f32 v204, v99, s0
	ds_write_b16 v200, v204 offset:224
	s_waitcnt lgkmcnt(0)
	ds_read_b128 v[208:211], v201
	v_lshl_add_u64 v[206:207], v[100:101], 0, v[202:203]
	s_waitcnt lgkmcnt(0)
	global_store_dwordx4 v[206:207], v[208:211], off

.LBB0_1304:
	s_or_b64 exec, exec, s[76:77]
	s_waitcnt lgkmcnt(5)
	v_add_f32_e32 v98, v171, v172
	v_fmamk_f32 v98, v98, 0x3b800000, v226
	v_rsq_f32_e32 v98, v98
	v_and_b32_e32 v102, 0xfff, v152
	v_ashrrev_i32_e32 v99, 9, v152
	v_and_b32_e32 v103, -8, v99
	v_pk_mul_f32 v[100:101], v[92:93], v[98:99] op_sel_hi:[1,0]
	v_pk_mul_f32 v[94:95], v[94:95], v[98:99] op_sel_hi:[1,0]
	v_pk_mul_f32 v[92:93], v[88:89], v[98:99] op_sel_hi:[1,0]
	v_pk_mul_f32 v[90:91], v[90:91], v[98:99] op_sel_hi:[1,0]
	v_lshlrev_b32_e32 v88, 1, v102
	s_and_saveexec_b64 s[22:23], s[8:9]
	s_xor_b64 s[76:77], exec, s[22:23]
	s_cbranch_execz .LBB0_1306
	v_add_u32_e32 v104, v143, v103
	v_ashrrev_i32_e32 v105, 31, v104
	v_lshlrev_b64 v[104:105], 19, v[104:105]
	v_lshl_add_u64 v[104:105], s[54:55], 0, v[104:105]
	v_mov_b32_e32 v123, v97
	v_lshl_add_u64 v[104:105], v[104:105], 0, v[122:123]
	v_mov_b32_e32 v89, v97
	v_lshl_add_u64 v[104:105], v[104:105], 0, v[88:89]
	s_movk_i32 s22, 0x4000
	s_movk_i32 s22, 0x6000
	v_cvt_pk_bf16_f32 v204, v100, s0
	ds_write_b16 v200, v204
	v_cvt_pk_bf16_f32 v204, v101, s0
	ds_write_b16 v200, v204 offset:32
	v_cvt_pk_bf16_f32 v204, v94, s0
	ds_write_b16 v200, v204 offset:64
	v_cvt_pk_bf16_f32 v204, v95, s0
	ds_write_b16 v200, v204 offset:96
	v_cvt_pk_bf16_f32 v204, v92, s0
	ds_write_b16 v200, v204 offset:128
	v_cvt_pk_bf16_f32 v204, v93, s0
	ds_write_b16 v200, v204 offset:160
	v_cvt_pk_bf16_f32 v204, v90, s0
	ds_write_b16 v200, v204 offset:192
	v_cvt_pk_bf16_f32 v204, v91, s0
	ds_write_b16 v200, v204 offset:224
	s_waitcnt lgkmcnt(0)
	ds_read_b128 v[208:211], v201
	v_lshl_add_u64 v[206:207], v[104:105], 0, v[202:203]
	s_waitcnt lgkmcnt(0)
	global_store_dwordx4 v[206:207], v[208:211], off

.LBB0_1308:
	s_or_b64 exec, exec, s[76:77]
	v_mov_b32_e32 v99, v98
	v_pk_mul_f32 v[90:91], v[84:85], v[98:99]
	v_pk_mul_f32 v[86:87], v[86:87], v[98:99]
	v_pk_mul_f32 v[84:85], v[80:81], v[98:99]
	v_pk_mul_f32 v[80:81], v[82:83], v[98:99]
	s_and_saveexec_b64 s[22:23], s[10:11]
	s_xor_b64 s[76:77], exec, s[22:23]
	s_cbranch_execz .LBB0_1310
	v_add_u32_e32 v82, v128, v103
	v_ashrrev_i32_e32 v83, 31, v82
	v_lshlrev_b64 v[82:83], 19, v[82:83]
	v_lshl_add_u64 v[82:83], s[54:55], 0, v[82:83]
	v_mov_b32_e32 v123, v97
	v_lshl_add_u64 v[82:83], v[82:83], 0, v[122:123]
	v_mov_b32_e32 v89, v97
	v_lshl_add_u64 v[82:83], v[82:83], 0, v[88:89]
	s_movk_i32 s22, 0x4000
	s_movk_i32 s22, 0x6000
	v_cvt_pk_bf16_f32 v204, v90, s0
	ds_write_b16 v200, v204
	v_cvt_pk_bf16_f32 v204, v91, s0
	ds_write_b16 v200, v204 offset:32
	v_cvt_pk_bf16_f32 v204, v86, s0
	ds_write_b16 v200, v204 offset:64
	v_cvt_pk_bf16_f32 v204, v87, s0
	ds_write_b16 v200, v204 offset:96
	v_cvt_pk_bf16_f32 v204, v84, s0
	ds_write_b16 v200, v204 offset:128
	v_cvt_pk_bf16_f32 v204, v85, s0
	ds_write_b16 v200, v204 offset:160
	v_cvt_pk_bf16_f32 v204, v80, s0
	ds_write_b16 v200, v204 offset:192
	v_cvt_pk_bf16_f32 v204, v81, s0
	ds_write_b16 v200, v204 offset:224
	s_waitcnt lgkmcnt(0)
	ds_read_b128 v[208:211], v201
	v_lshl_add_u64 v[206:207], v[82:83], 0, v[202:203]
	s_waitcnt lgkmcnt(0)
	global_store_dwordx4 v[206:207], v[208:211], off

.LBB0_1312:
	s_or_b64 exec, exec, s[76:77]
	s_waitcnt lgkmcnt(4)
	v_add_f32_e32 v80, v169, v170
	v_fmamk_f32 v80, v80, 0x3b800000, v226
	v_rsq_f32_e32 v80, v80
	v_and_b32_e32 v84, 0xfff, v150
	v_ashrrev_i32_e32 v81, 9, v150
	v_and_b32_e32 v85, -8, v81
	v_pk_mul_f32 v[82:83], v[76:77], v[80:81] op_sel_hi:[1,0]
	v_pk_mul_f32 v[78:79], v[78:79], v[80:81] op_sel_hi:[1,0]
	v_pk_mul_f32 v[76:77], v[72:73], v[80:81] op_sel_hi:[1,0]
	v_pk_mul_f32 v[74:75], v[74:75], v[80:81] op_sel_hi:[1,0]
	v_lshlrev_b32_e32 v72, 1, v84
	s_and_saveexec_b64 s[22:23], s[8:9]
	s_xor_b64 s[76:77], exec, s[22:23]
	s_cbranch_execz .LBB0_1314
	v_add_u32_e32 v86, v143, v85
	v_ashrrev_i32_e32 v87, 31, v86
	v_lshlrev_b64 v[86:87], 19, v[86:87]
	v_lshl_add_u64 v[86:87], s[54:55], 0, v[86:87]
	v_mov_b32_e32 v123, v97
	v_lshl_add_u64 v[86:87], v[86:87], 0, v[122:123]
	v_mov_b32_e32 v73, v97
	v_lshl_add_u64 v[86:87], v[86:87], 0, v[72:73]
	s_movk_i32 s22, 0x4000
	s_movk_i32 s22, 0x6000
	v_cvt_pk_bf16_f32 v204, v82, s0
	ds_write_b16 v200, v204
	v_cvt_pk_bf16_f32 v204, v83, s0
	ds_write_b16 v200, v204 offset:32
	v_cvt_pk_bf16_f32 v204, v78, s0
	ds_write_b16 v200, v204 offset:64
	v_cvt_pk_bf16_f32 v204, v79, s0
	ds_write_b16 v200, v204 offset:96
	v_cvt_pk_bf16_f32 v204, v76, s0
	ds_write_b16 v200, v204 offset:128
	v_cvt_pk_bf16_f32 v204, v77, s0
	ds_write_b16 v200, v204 offset:160
	v_cvt_pk_bf16_f32 v204, v74, s0
	ds_write_b16 v200, v204 offset:192
	v_cvt_pk_bf16_f32 v204, v75, s0
	ds_write_b16 v200, v204 offset:224
	s_waitcnt lgkmcnt(0)
	ds_read_b128 v[208:211], v201
	v_lshl_add_u64 v[206:207], v[86:87], 0, v[202:203]
	s_waitcnt lgkmcnt(0)
	global_store_dwordx4 v[206:207], v[208:211], off

.LBB0_1316:
	s_or_b64 exec, exec, s[76:77]
	v_mov_b32_e32 v81, v80
	v_pk_mul_f32 v[74:75], v[68:69], v[80:81]
	v_pk_mul_f32 v[70:71], v[70:71], v[80:81]
	v_pk_mul_f32 v[68:69], v[64:65], v[80:81]
	v_pk_mul_f32 v[64:65], v[66:67], v[80:81]
	s_and_saveexec_b64 s[22:23], s[10:11]
	s_xor_b64 s[76:77], exec, s[22:23]
	s_cbranch_execz .LBB0_1318
	v_add_u32_e32 v66, v128, v85
	v_ashrrev_i32_e32 v67, 31, v66
	v_lshlrev_b64 v[66:67], 19, v[66:67]
	v_lshl_add_u64 v[66:67], s[54:55], 0, v[66:67]
	v_mov_b32_e32 v123, v97
	v_lshl_add_u64 v[66:67], v[66:67], 0, v[122:123]
	v_mov_b32_e32 v73, v97
	v_lshl_add_u64 v[66:67], v[66:67], 0, v[72:73]
	s_movk_i32 s22, 0x4000
	s_movk_i32 s22, 0x6000
	v_cvt_pk_bf16_f32 v204, v74, s0
	ds_write_b16 v200, v204
	v_cvt_pk_bf16_f32 v204, v75, s0
	ds_write_b16 v200, v204 offset:32
	v_cvt_pk_bf16_f32 v204, v70, s0
	ds_write_b16 v200, v204 offset:64
	v_cvt_pk_bf16_f32 v204, v71, s0
	ds_write_b16 v200, v204 offset:96
	v_cvt_pk_bf16_f32 v204, v68, s0
	ds_write_b16 v200, v204 offset:128
	v_cvt_pk_bf16_f32 v204, v69, s0
	ds_write_b16 v200, v204 offset:160
	v_cvt_pk_bf16_f32 v204, v64, s0
	ds_write_b16 v200, v204 offset:192
	v_cvt_pk_bf16_f32 v204, v65, s0
	ds_write_b16 v200, v204 offset:224
	s_waitcnt lgkmcnt(0)
	ds_read_b128 v[208:211], v201
	v_lshl_add_u64 v[206:207], v[66:67], 0, v[202:203]
	s_waitcnt lgkmcnt(0)
	global_store_dwordx4 v[206:207], v[208:211], off

.LBB0_1320:
	s_or_b64 exec, exec, s[76:77]
	s_waitcnt lgkmcnt(3)
	v_add_f32_e32 v64, v167, v168
	v_fmamk_f32 v64, v64, 0x3b800000, v226
	v_rsq_f32_e32 v64, v64
	v_and_b32_e32 v68, 0xfff, v148
	v_ashrrev_i32_e32 v65, 9, v148
	v_and_b32_e32 v69, -8, v65
	v_pk_mul_f32 v[66:67], v[60:61], v[64:65] op_sel_hi:[1,0]
	v_pk_mul_f32 v[62:63], v[62:63], v[64:65] op_sel_hi:[1,0]
	v_pk_mul_f32 v[60:61], v[56:57], v[64:65] op_sel_hi:[1,0]
	v_pk_mul_f32 v[58:59], v[58:59], v[64:65] op_sel_hi:[1,0]
	v_lshlrev_b32_e32 v56, 1, v68
	s_and_saveexec_b64 s[22:23], s[8:9]
	s_xor_b64 s[76:77], exec, s[22:23]
	s_cbranch_execz .LBB0_1322
	v_add_u32_e32 v70, v143, v69
	v_ashrrev_i32_e32 v71, 31, v70
	v_lshlrev_b64 v[70:71], 19, v[70:71]
	v_lshl_add_u64 v[70:71], s[54:55], 0, v[70:71]
	v_mov_b32_e32 v123, v97
	v_lshl_add_u64 v[70:71], v[70:71], 0, v[122:123]
	v_mov_b32_e32 v57, v97
	v_lshl_add_u64 v[70:71], v[70:71], 0, v[56:57]
	s_movk_i32 s22, 0x4000
	s_movk_i32 s22, 0x6000
	v_cvt_pk_bf16_f32 v204, v66, s0
	ds_write_b16 v200, v204
	v_cvt_pk_bf16_f32 v204, v67, s0
	ds_write_b16 v200, v204 offset:32
	v_cvt_pk_bf16_f32 v204, v62, s0
	ds_write_b16 v200, v204 offset:64
	v_cvt_pk_bf16_f32 v204, v63, s0
	ds_write_b16 v200, v204 offset:96
	v_cvt_pk_bf16_f32 v204, v60, s0
	ds_write_b16 v200, v204 offset:128
	v_cvt_pk_bf16_f32 v204, v61, s0
	ds_write_b16 v200, v204 offset:160
	v_cvt_pk_bf16_f32 v204, v58, s0
	ds_write_b16 v200, v204 offset:192
	v_cvt_pk_bf16_f32 v204, v59, s0
	ds_write_b16 v200, v204 offset:224
	s_waitcnt lgkmcnt(0)
	ds_read_b128 v[208:211], v201
	v_lshl_add_u64 v[206:207], v[70:71], 0, v[202:203]
	s_waitcnt lgkmcnt(0)
	global_store_dwordx4 v[206:207], v[208:211], off

.LBB0_1324:
	s_or_b64 exec, exec, s[76:77]
	v_mov_b32_e32 v65, v64
	v_pk_mul_f32 v[58:59], v[52:53], v[64:65]
	v_pk_mul_f32 v[54:55], v[54:55], v[64:65]
	v_pk_mul_f32 v[52:53], v[48:49], v[64:65]
	v_pk_mul_f32 v[48:49], v[50:51], v[64:65]
	s_and_saveexec_b64 s[22:23], s[10:11]
	s_xor_b64 s[76:77], exec, s[22:23]
	s_cbranch_execz .LBB0_1326
	v_add_u32_e32 v50, v128, v69
	v_ashrrev_i32_e32 v51, 31, v50
	v_lshlrev_b64 v[50:51], 19, v[50:51]
	v_lshl_add_u64 v[50:51], s[54:55], 0, v[50:51]
	v_mov_b32_e32 v123, v97
	v_lshl_add_u64 v[50:51], v[50:51], 0, v[122:123]
	v_mov_b32_e32 v57, v97
	v_lshl_add_u64 v[50:51], v[50:51], 0, v[56:57]
	s_movk_i32 s22, 0x4000
	s_movk_i32 s22, 0x6000
	v_cvt_pk_bf16_f32 v204, v58, s0
	ds_write_b16 v200, v204
	v_cvt_pk_bf16_f32 v204, v59, s0
	ds_write_b16 v200, v204 offset:32
	v_cvt_pk_bf16_f32 v204, v54, s0
	ds_write_b16 v200, v204 offset:64
	v_cvt_pk_bf16_f32 v204, v55, s0
	ds_write_b16 v200, v204 offset:96
	v_cvt_pk_bf16_f32 v204, v52, s0
	ds_write_b16 v200, v204 offset:128
	v_cvt_pk_bf16_f32 v204, v53, s0
	ds_write_b16 v200, v204 offset:160
	v_cvt_pk_bf16_f32 v204, v48, s0
	ds_write_b16 v200, v204 offset:192
	v_cvt_pk_bf16_f32 v204, v49, s0
	ds_write_b16 v200, v204 offset:224
	s_waitcnt lgkmcnt(0)
	ds_read_b128 v[208:211], v201
	v_lshl_add_u64 v[206:207], v[50:51], 0, v[202:203]
	s_waitcnt lgkmcnt(0)
	global_store_dwordx4 v[206:207], v[208:211], off

.LBB0_1328:
	s_or_b64 exec, exec, s[76:77]
	s_waitcnt lgkmcnt(2)
	v_add_f32_e32 v48, v155, v166
	v_fmamk_f32 v48, v48, 0x3b800000, v226
	v_rsq_f32_e32 v48, v48
	v_and_b32_e32 v52, 0xfff, v146
	v_ashrrev_i32_e32 v49, 9, v146
	v_and_b32_e32 v53, -8, v49
	v_pk_mul_f32 v[50:51], v[44:45], v[48:49] op_sel_hi:[1,0]
	v_pk_mul_f32 v[46:47], v[46:47], v[48:49] op_sel_hi:[1,0]
	v_pk_mul_f32 v[44:45], v[40:41], v[48:49] op_sel_hi:[1,0]
	v_pk_mul_f32 v[42:43], v[42:43], v[48:49] op_sel_hi:[1,0]
	v_lshlrev_b32_e32 v40, 1, v52
	s_and_saveexec_b64 s[22:23], s[8:9]
	s_xor_b64 s[76:77], exec, s[22:23]
	s_cbranch_execz .LBB0_1330
	v_add_u32_e32 v54, v143, v53
	v_ashrrev_i32_e32 v55, 31, v54
	v_lshlrev_b64 v[54:55], 19, v[54:55]
	v_lshl_add_u64 v[54:55], s[54:55], 0, v[54:55]
	v_mov_b32_e32 v123, v97
	v_lshl_add_u64 v[54:55], v[54:55], 0, v[122:123]
	v_mov_b32_e32 v41, v97
	v_lshl_add_u64 v[54:55], v[54:55], 0, v[40:41]
	s_movk_i32 s22, 0x4000
	s_movk_i32 s22, 0x6000
	v_cvt_pk_bf16_f32 v204, v50, s0
	ds_write_b16 v200, v204
	v_cvt_pk_bf16_f32 v204, v51, s0
	ds_write_b16 v200, v204 offset:32
	v_cvt_pk_bf16_f32 v204, v46, s0
	ds_write_b16 v200, v204 offset:64
	v_cvt_pk_bf16_f32 v204, v47, s0
	ds_write_b16 v200, v204 offset:96
	v_cvt_pk_bf16_f32 v204, v44, s0
	ds_write_b16 v200, v204 offset:128
	v_cvt_pk_bf16_f32 v204, v45, s0
	ds_write_b16 v200, v204 offset:160
	v_cvt_pk_bf16_f32 v204, v42, s0
	ds_write_b16 v200, v204 offset:192
	v_cvt_pk_bf16_f32 v204, v43, s0
	ds_write_b16 v200, v204 offset:224
	s_waitcnt lgkmcnt(0)
	ds_read_b128 v[208:211], v201
	v_lshl_add_u64 v[206:207], v[54:55], 0, v[202:203]
	s_waitcnt lgkmcnt(0)
	global_store_dwordx4 v[206:207], v[208:211], off

.LBB0_1332:
	s_or_b64 exec, exec, s[76:77]
	v_mov_b32_e32 v49, v48
	v_pk_mul_f32 v[42:43], v[36:37], v[48:49]
	v_pk_mul_f32 v[38:39], v[38:39], v[48:49]
	v_pk_mul_f32 v[36:37], v[32:33], v[48:49]
	v_pk_mul_f32 v[32:33], v[34:35], v[48:49]
	s_and_saveexec_b64 s[22:23], s[10:11]
	s_xor_b64 s[76:77], exec, s[22:23]
	s_cbranch_execz .LBB0_1334
	v_add_u32_e32 v34, v128, v53
	v_ashrrev_i32_e32 v35, 31, v34
	v_lshlrev_b64 v[34:35], 19, v[34:35]
	v_lshl_add_u64 v[34:35], s[54:55], 0, v[34:35]
	v_mov_b32_e32 v123, v97
	v_lshl_add_u64 v[34:35], v[34:35], 0, v[122:123]
	v_mov_b32_e32 v41, v97
	v_lshl_add_u64 v[34:35], v[34:35], 0, v[40:41]
	s_movk_i32 s22, 0x4000
	s_movk_i32 s22, 0x6000
	v_cvt_pk_bf16_f32 v204, v42, s0
	ds_write_b16 v200, v204
	v_cvt_pk_bf16_f32 v204, v43, s0
	ds_write_b16 v200, v204 offset:32
	v_cvt_pk_bf16_f32 v204, v38, s0
	ds_write_b16 v200, v204 offset:64
	v_cvt_pk_bf16_f32 v204, v39, s0
	ds_write_b16 v200, v204 offset:96
	v_cvt_pk_bf16_f32 v204, v36, s0
	ds_write_b16 v200, v204 offset:128
	v_cvt_pk_bf16_f32 v204, v37, s0
	ds_write_b16 v200, v204 offset:160
	v_cvt_pk_bf16_f32 v204, v32, s0
	ds_write_b16 v200, v204 offset:192
	v_cvt_pk_bf16_f32 v204, v33, s0
	ds_write_b16 v200, v204 offset:224
	s_waitcnt lgkmcnt(0)
	ds_read_b128 v[208:211], v201
	v_lshl_add_u64 v[206:207], v[34:35], 0, v[202:203]
	s_waitcnt lgkmcnt(0)
	global_store_dwordx4 v[206:207], v[208:211], off

.LBB0_1336:
	s_or_b64 exec, exec, s[76:77]
	s_waitcnt lgkmcnt(1)
	v_add_f32_e32 v32, v151, v153
	v_fmamk_f32 v32, v32, 0x3b800000, v226
	v_rsq_f32_e32 v32, v32
	v_and_b32_e32 v36, 0xfff, v144
	v_ashrrev_i32_e32 v33, 9, v144
	v_and_b32_e32 v37, -8, v33
	v_pk_mul_f32 v[34:35], v[28:29], v[32:33] op_sel_hi:[1,0]
	v_pk_mul_f32 v[30:31], v[30:31], v[32:33] op_sel_hi:[1,0]
	v_pk_mul_f32 v[28:29], v[24:25], v[32:33] op_sel_hi:[1,0]
	v_pk_mul_f32 v[26:27], v[26:27], v[32:33] op_sel_hi:[1,0]
	v_lshlrev_b32_e32 v24, 1, v36
	s_and_saveexec_b64 s[22:23], s[8:9]
	s_xor_b64 s[76:77], exec, s[22:23]
	s_cbranch_execz .LBB0_1338
	v_add_u32_e32 v38, v143, v37
	v_ashrrev_i32_e32 v39, 31, v38
	v_lshlrev_b64 v[38:39], 19, v[38:39]
	v_lshl_add_u64 v[38:39], s[54:55], 0, v[38:39]
	v_mov_b32_e32 v123, v97
	v_lshl_add_u64 v[38:39], v[38:39], 0, v[122:123]
	v_mov_b32_e32 v25, v97
	v_lshl_add_u64 v[38:39], v[38:39], 0, v[24:25]
	s_movk_i32 s22, 0x4000
	s_movk_i32 s22, 0x6000
	v_cvt_pk_bf16_f32 v204, v34, s0
	ds_write_b16 v200, v204
	v_cvt_pk_bf16_f32 v204, v35, s0
	ds_write_b16 v200, v204 offset:32
	v_cvt_pk_bf16_f32 v204, v30, s0
	ds_write_b16 v200, v204 offset:64
	v_cvt_pk_bf16_f32 v204, v31, s0
	ds_write_b16 v200, v204 offset:96
	v_cvt_pk_bf16_f32 v204, v28, s0
	ds_write_b16 v200, v204 offset:128
	v_cvt_pk_bf16_f32 v204, v29, s0
	ds_write_b16 v200, v204 offset:160
	v_cvt_pk_bf16_f32 v204, v26, s0
	ds_write_b16 v200, v204 offset:192
	v_cvt_pk_bf16_f32 v204, v27, s0
	ds_write_b16 v200, v204 offset:224
	s_waitcnt lgkmcnt(0)
	ds_read_b128 v[208:211], v201
	v_lshl_add_u64 v[206:207], v[38:39], 0, v[202:203]
	s_waitcnt lgkmcnt(0)
	global_store_dwordx4 v[206:207], v[208:211], off

.LBB0_1340:
	s_or_b64 exec, exec, s[76:77]
	v_mov_b32_e32 v33, v32
	v_pk_mul_f32 v[26:27], v[20:21], v[32:33]
	v_pk_mul_f32 v[22:23], v[22:23], v[32:33]
	v_pk_mul_f32 v[20:21], v[16:17], v[32:33]
	v_pk_mul_f32 v[16:17], v[18:19], v[32:33]
	s_and_saveexec_b64 s[22:23], s[10:11]
	s_xor_b64 s[76:77], exec, s[22:23]
	s_cbranch_execz .LBB0_1342
	v_add_u32_e32 v18, v128, v37
	v_ashrrev_i32_e32 v19, 31, v18
	v_lshlrev_b64 v[18:19], 19, v[18:19]
	v_lshl_add_u64 v[18:19], s[54:55], 0, v[18:19]
	v_mov_b32_e32 v123, v97
	v_lshl_add_u64 v[18:19], v[18:19], 0, v[122:123]
	v_mov_b32_e32 v25, v97
	v_lshl_add_u64 v[18:19], v[18:19], 0, v[24:25]
	s_movk_i32 s22, 0x4000
	s_movk_i32 s22, 0x6000
	v_cvt_pk_bf16_f32 v204, v26, s0
	ds_write_b16 v200, v204
	v_cvt_pk_bf16_f32 v204, v27, s0
	ds_write_b16 v200, v204 offset:32
	v_cvt_pk_bf16_f32 v204, v22, s0
	ds_write_b16 v200, v204 offset:64
	v_cvt_pk_bf16_f32 v204, v23, s0
	ds_write_b16 v200, v204 offset:96
	v_cvt_pk_bf16_f32 v204, v20, s0
	ds_write_b16 v200, v204 offset:128
	v_cvt_pk_bf16_f32 v204, v21, s0
	ds_write_b16 v200, v204 offset:160
	v_cvt_pk_bf16_f32 v204, v16, s0
	ds_write_b16 v200, v204 offset:192
	v_cvt_pk_bf16_f32 v204, v17, s0
	ds_write_b16 v200, v204 offset:224
	s_waitcnt lgkmcnt(0)
	ds_read_b128 v[208:211], v201
	v_lshl_add_u64 v[206:207], v[18:19], 0, v[202:203]
	s_waitcnt lgkmcnt(0)
	global_store_dwordx4 v[206:207], v[208:211], off

.LBB0_1344:
	s_or_b64 exec, exec, s[76:77]
	s_waitcnt lgkmcnt(0)
	v_add_f32_e32 v16, v145, v147
	v_fmamk_f32 v16, v16, 0x3b800000, v226
	v_rsq_f32_e32 v16, v16
	v_and_b32_e32 v20, 0xfff, v142
	v_ashrrev_i32_e32 v17, 9, v142
	v_and_b32_e32 v21, -8, v17
	v_pk_mul_f32 v[18:19], v[12:13], v[16:17] op_sel_hi:[1,0]
	v_pk_mul_f32 v[14:15], v[14:15], v[16:17] op_sel_hi:[1,0]
	v_pk_mul_f32 v[12:13], v[8:9], v[16:17] op_sel_hi:[1,0]
	v_pk_mul_f32 v[10:11], v[10:11], v[16:17] op_sel_hi:[1,0]
	v_lshlrev_b32_e32 v8, 1, v20
	s_and_saveexec_b64 s[22:23], s[8:9]
	s_xor_b64 s[8:9], exec, s[22:23]
	s_cbranch_execz .LBB0_1346
	v_add_u32_e32 v22, v143, v21
	v_ashrrev_i32_e32 v23, 31, v22
	v_lshlrev_b64 v[22:23], 19, v[22:23]
	v_lshl_add_u64 v[22:23], s[54:55], 0, v[22:23]
	v_mov_b32_e32 v123, v97
	v_lshl_add_u64 v[22:23], v[22:23], 0, v[122:123]
	v_mov_b32_e32 v9, v97
	v_lshl_add_u64 v[22:23], v[22:23], 0, v[8:9]
	s_movk_i32 s22, 0x4000
	s_movk_i32 s22, 0x6000
	v_cvt_pk_bf16_f32 v204, v18, s0
	ds_write_b16 v200, v204
	v_cvt_pk_bf16_f32 v204, v19, s0
	ds_write_b16 v200, v204 offset:32
	v_cvt_pk_bf16_f32 v204, v14, s0
	ds_write_b16 v200, v204 offset:64
	v_cvt_pk_bf16_f32 v204, v15, s0
	ds_write_b16 v200, v204 offset:96
	v_cvt_pk_bf16_f32 v204, v12, s0
	ds_write_b16 v200, v204 offset:128
	v_cvt_pk_bf16_f32 v204, v13, s0
	ds_write_b16 v200, v204 offset:160
	v_cvt_pk_bf16_f32 v204, v10, s0
	ds_write_b16 v200, v204 offset:192
	v_cvt_pk_bf16_f32 v204, v11, s0
	ds_write_b16 v200, v204 offset:224
	s_waitcnt lgkmcnt(0)
	ds_read_b128 v[208:211], v201
	v_lshl_add_u64 v[206:207], v[22:23], 0, v[202:203]
	s_waitcnt lgkmcnt(0)
	global_store_dwordx4 v[206:207], v[208:211], off

.LBB0_1348:
	s_or_b64 exec, exec, s[8:9]
	v_mov_b32_e32 v17, v16
	v_pk_mul_f32 v[10:11], v[4:5], v[16:17]
	v_pk_mul_f32 v[6:7], v[6:7], v[16:17]
	v_pk_mul_f32 v[4:5], v[0:1], v[16:17]
	v_pk_mul_f32 v[0:1], v[2:3], v[16:17]
	s_and_saveexec_b64 s[8:9], s[10:11]
	s_xor_b64 s[8:9], exec, s[8:9]
	s_cbranch_execz .LBB0_1351
	v_add_u32_e32 v2, v128, v21
	v_ashrrev_i32_e32 v3, 31, v2
	v_lshlrev_b64 v[2:3], 19, v[2:3]
	v_lshl_add_u64 v[2:3], s[54:55], 0, v[2:3]
	v_mov_b32_e32 v123, v97
	v_lshl_add_u64 v[2:3], v[2:3], 0, v[122:123]
	v_mov_b32_e32 v9, v97
	v_lshl_add_u64 v[2:3], v[2:3], 0, v[8:9]
	s_movk_i32 s10, 0x4000
	s_movk_i32 s10, 0x6000
	v_cvt_pk_bf16_f32 v204, v10, s0
	ds_write_b16 v200, v204
	v_cvt_pk_bf16_f32 v204, v11, s0
	ds_write_b16 v200, v204 offset:32
	v_cvt_pk_bf16_f32 v204, v6, s0
	ds_write_b16 v200, v204 offset:64
	v_cvt_pk_bf16_f32 v204, v7, s0
	ds_write_b16 v200, v204 offset:96
	v_cvt_pk_bf16_f32 v204, v4, s0
	ds_write_b16 v200, v204 offset:128
	v_cvt_pk_bf16_f32 v204, v5, s0
	ds_write_b16 v200, v204 offset:160
	v_cvt_pk_bf16_f32 v204, v0, s0
	ds_write_b16 v200, v204 offset:192
	v_cvt_pk_bf16_f32 v204, v1, s0
	ds_write_b16 v200, v204 offset:224
	s_waitcnt lgkmcnt(0)
	ds_read_b128 v[208:211], v201
	v_lshl_add_u64 v[206:207], v[2:3], 0, v[202:203]
	s_waitcnt lgkmcnt(0)
	global_store_dwordx4 v[206:207], v[208:211], off
